# SP1 phases of all four large GEMM K-loops: LDS-DMA issued between the B-fragment and A-fragment ds_reads
# speedup vs baseline: 1.0041x; 1.0013x over previous
.LBB0_230:
	s_add_i32 s74, s58, 2
	s_add_u32 s75, s56, 0x80
	s_addc_u32 s59, s57, 0
	s_add_i32 s78, 0, 0x10000
	s_cmp_eq_u32 s66, s58
	s_cselect_b32 s59, s29, s59
	s_cselect_b32 s58, s50, s75
	s_cselect_b32 s81, s45, s55
	s_cselect_b32 s80, s44, s51
	s_add_i32 s75, 0, 0x14000
	v_add_u32_e32 v156, s78, v146
	v_add_u32_e32 v172, s75, v146
	ds_read_b128 v[140:143], v156
	ds_read_b128 v[148:151], v156 offset:1024
	ds_read_b128 v[152:155], v156 offset:2048
	ds_read_b128 v[156:159], v156 offset:3072
	ds_read_b128 v[160:163], v172
	ds_read_b128 v[164:167], v172 offset:1024
	ds_read_b128 v[168:171], v172 offset:2048
	ds_read_b128 v[172:175], v172 offset:3072
	v_lshl_add_u64 v[188:189], s[56:57], 0, v[134:135]
	s_mov_b32 m0, s64
	s_nop 0
	global_load_lds_dwordx4 v[188:189], off
	v_lshl_add_u64 v[188:189], s[56:57], 0, v[132:133]
	s_mov_b32 m0, s65
	s_nop 0
	global_load_lds_dwordx4 v[188:189], off
	v_lshl_add_u64 v[188:189], s[56:57], 0, v[136:137]
	s_add_i32 m0, s27, 0xc000
	s_nop 0
	global_load_lds_dwordx4 v[188:189], off
	v_lshl_add_u64 v[188:189], s[56:57], 0, v[138:139]
	s_add_i32 m0, s27, 0xe000
	s_nop 0
	global_load_lds_dwordx4 v[188:189], off
	ds_read_b128 v[176:179], v147
	ds_read_b128 v[180:183], v147 offset:1024
	ds_read_b128 v[184:187], v147 offset:2048
	ds_read_b128 v[200:203], v147 offset:3072
	ds_read_b128 v[204:207], v147 offset:4096
	ds_read_b128 v[208:211], v147 offset:5120
	ds_read_b128 v[212:215], v147 offset:6144
	ds_read_b128 v[216:219], v147 offset:7168
	s_waitcnt vmcnt(8)
	s_waitcnt lgkmcnt(0)
	s_barrier
	s_setprio 1
	s_waitcnt lgkmcnt(0)
	v_mfma_f32_16x16x32_bf16 v[122:125], v[140:143], v[176:179], v[122:125]
	v_mfma_f32_16x16x32_bf16 v[126:129], v[152:155], v[176:179], v[126:129]
	v_mfma_f32_16x16x32_bf16 v[110:113], v[140:143], v[184:187], v[110:113]
	v_mfma_f32_16x16x32_bf16 v[106:109], v[152:155], v[184:187], v[106:109]
	v_mfma_f32_16x16x32_bf16 v[94:97], v[140:143], v[204:207], v[94:97]
	v_mfma_f32_16x16x32_bf16 v[90:93], v[152:155], v[204:207], v[90:93]
	v_mfma_f32_16x16x32_bf16 v[78:81], v[140:143], v[212:215], v[78:81]
	v_mfma_f32_16x16x32_bf16 v[74:77], v[152:155], v[212:215], v[74:77]
	v_mfma_f32_16x16x32_bf16 v[122:125], v[148:151], v[180:183], v[122:125]
	v_mfma_f32_16x16x32_bf16 v[126:129], v[156:159], v[180:183], v[126:129]
	v_mfma_f32_16x16x32_bf16 v[110:113], v[148:151], v[200:203], v[110:113]
	v_mfma_f32_16x16x32_bf16 v[106:109], v[156:159], v[200:203], v[106:109]
	v_mfma_f32_16x16x32_bf16 v[94:97], v[148:151], v[208:211], v[94:97]
	v_mfma_f32_16x16x32_bf16 v[90:93], v[156:159], v[208:211], v[90:93]
	v_mfma_f32_16x16x32_bf16 v[78:81], v[148:151], v[216:219], v[78:81]
	v_mfma_f32_16x16x32_bf16 v[74:77], v[156:159], v[216:219], v[74:77]
	s_setprio 0
	s_setprio 1
	v_mfma_f32_16x16x32_bf16 v[118:121], v[160:163], v[176:179], v[118:121]
	v_mfma_f32_16x16x32_bf16 v[114:117], v[168:171], v[176:179], v[114:117]
	v_mfma_f32_16x16x32_bf16 v[102:105], v[160:163], v[184:187], v[102:105]
	v_mfma_f32_16x16x32_bf16 v[98:101], v[168:171], v[184:187], v[98:101]
	v_mfma_f32_16x16x32_bf16 v[86:89], v[160:163], v[204:207], v[86:89]
	v_mfma_f32_16x16x32_bf16 v[82:85], v[168:171], v[204:207], v[82:85]
	v_mfma_f32_16x16x32_bf16 v[70:73], v[160:163], v[212:215], v[70:73]
	v_mfma_f32_16x16x32_bf16 v[66:69], v[168:171], v[212:215], v[66:69]
	v_mfma_f32_16x16x32_bf16 v[118:121], v[164:167], v[180:183], v[118:121]
	v_mfma_f32_16x16x32_bf16 v[114:117], v[172:175], v[180:183], v[114:117]
	v_mfma_f32_16x16x32_bf16 v[102:105], v[164:167], v[200:203], v[102:105]
	v_mfma_f32_16x16x32_bf16 v[98:101], v[172:175], v[200:203], v[98:101]
	v_mfma_f32_16x16x32_bf16 v[86:89], v[164:167], v[208:211], v[86:89]
	v_mfma_f32_16x16x32_bf16 v[82:85], v[172:175], v[208:211], v[82:85]
	v_mfma_f32_16x16x32_bf16 v[70:73], v[164:167], v[216:219], v[70:73]
	v_mfma_f32_16x16x32_bf16 v[66:69], v[172:175], v[216:219], v[66:69]
	s_setprio 0
	s_barrier
	s_add_i32 s78, s78, s5
	v_lshl_add_u64 v[188:189], s[80:81], 0, v[0:1]
	s_mov_b32 m0, s78
	ds_read_b128 v[176:179], v147 offset:16384
	ds_read_b128 v[180:183], v147 offset:17408
	ds_read_b128 v[184:187], v147 offset:18432
	ds_read_b128 v[200:203], v147 offset:19456
	ds_read_b128 v[204:207], v147 offset:20480
	ds_read_b128 v[208:211], v147 offset:21504
	ds_read_b128 v[212:215], v147 offset:22528
	ds_read_b128 v[216:219], v147 offset:23552
	global_load_lds_dwordx4 v[188:189], off
	s_add_i32 m0, s78, 0x2000
	v_lshl_add_u64 v[220:221], s[80:81], 0, v[130:131]
	s_add_u32 s80, s80, s6
	s_addc_u32 s81, s81, s7
	s_add_i32 s75, s75, s5
	global_load_lds_dwordx4 v[220:221], off
	v_lshl_add_u64 v[222:223], s[80:81], 0, v[0:1]
	s_mov_b32 m0, s75
	v_lshl_add_u64 v[224:225], s[80:81], 0, v[130:131]
	global_load_lds_dwordx4 v[222:223], off
	s_add_i32 m0, s75, 0x2000
	v_lshl_add_u64 v[226:227], s[58:59], 0, v[134:135]
	global_load_lds_dwordx4 v[224:225], off
	v_lshl_add_u64 v[228:229], s[58:59], 0, v[132:133]
	s_waitcnt vmcnt(6)
	s_waitcnt lgkmcnt(0)
	s_barrier
	s_setprio 1
	s_waitcnt lgkmcnt(0)
	v_mfma_f32_16x16x32_bf16 v[62:65], v[140:143], v[176:179], v[62:65]
	v_mfma_f32_16x16x32_bf16 v[58:61], v[152:155], v[176:179], v[58:61]
	v_mfma_f32_16x16x32_bf16 v[46:49], v[140:143], v[184:187], v[46:49]
	v_mfma_f32_16x16x32_bf16 v[42:45], v[152:155], v[184:187], v[42:45]
	v_mfma_f32_16x16x32_bf16 v[30:33], v[140:143], v[204:207], v[30:33]
	v_mfma_f32_16x16x32_bf16 v[26:29], v[152:155], v[204:207], v[26:29]
	v_mfma_f32_16x16x32_bf16 v[14:17], v[140:143], v[212:215], v[14:17]
	v_mfma_f32_16x16x32_bf16 v[10:13], v[152:155], v[212:215], v[10:13]
	v_mfma_f32_16x16x32_bf16 v[62:65], v[148:151], v[180:183], v[62:65]
	v_mfma_f32_16x16x32_bf16 v[58:61], v[156:159], v[180:183], v[58:61]
	v_mfma_f32_16x16x32_bf16 v[46:49], v[148:151], v[200:203], v[46:49]
	v_mfma_f32_16x16x32_bf16 v[42:45], v[156:159], v[200:203], v[42:45]
	v_mfma_f32_16x16x32_bf16 v[30:33], v[148:151], v[208:211], v[30:33]
	v_mfma_f32_16x16x32_bf16 v[26:29], v[156:159], v[208:211], v[26:29]
	v_mfma_f32_16x16x32_bf16 v[14:17], v[148:151], v[216:219], v[14:17]
	v_mfma_f32_16x16x32_bf16 v[10:13], v[156:159], v[216:219], v[10:13]
	s_setprio 0
	s_setprio 1
	v_mfma_f32_16x16x32_bf16 v[54:57], v[160:163], v[176:179], v[54:57]
	v_mfma_f32_16x16x32_bf16 v[50:53], v[168:171], v[176:179], v[50:53]
	v_mfma_f32_16x16x32_bf16 v[38:41], v[160:163], v[184:187], v[38:41]
	v_mfma_f32_16x16x32_bf16 v[34:37], v[168:171], v[184:187], v[34:37]
	v_mfma_f32_16x16x32_bf16 v[22:25], v[160:163], v[204:207], v[22:25]
	v_mfma_f32_16x16x32_bf16 v[18:21], v[168:171], v[204:207], v[18:21]
	v_mfma_f32_16x16x32_bf16 v[6:9], v[160:163], v[212:215], v[6:9]
	v_mfma_f32_16x16x32_bf16 v[2:5], v[168:171], v[212:215], v[2:5]
	v_mfma_f32_16x16x32_bf16 v[54:57], v[164:167], v[180:183], v[54:57]
	v_mfma_f32_16x16x32_bf16 v[50:53], v[172:175], v[180:183], v[50:53]
	v_mfma_f32_16x16x32_bf16 v[38:41], v[164:167], v[200:203], v[38:41]
	v_mfma_f32_16x16x32_bf16 v[34:37], v[172:175], v[200:203], v[34:37]
	v_mfma_f32_16x16x32_bf16 v[22:25], v[164:167], v[208:211], v[22:25]
	v_mfma_f32_16x16x32_bf16 v[18:21], v[172:175], v[208:211], v[18:21]
	v_mfma_f32_16x16x32_bf16 v[6:9], v[164:167], v[216:219], v[6:9]
	v_mfma_f32_16x16x32_bf16 v[2:5], v[172:175], v[216:219], v[2:5]
	s_setprio 0
	s_barrier
	s_add_i32 s75, 0, 0x18000
	s_add_i32 s78, 0, 0x1c000
	v_add_u32_e32 v156, s75, v146
	v_add_u32_e32 v172, s78, v146
	ds_read_b128 v[140:143], v156
	ds_read_b128 v[148:151], v156 offset:1024
	ds_read_b128 v[152:155], v156 offset:2048
	ds_read_b128 v[156:159], v156 offset:3072
	ds_read_b128 v[160:163], v172
	ds_read_b128 v[164:167], v172 offset:1024
	ds_read_b128 v[168:171], v172 offset:2048
	ds_read_b128 v[172:175], v172 offset:3072
	s_add_u32 s58, s58, s2
	s_addc_u32 s59, s59, s3
	s_mov_b32 m0, s27
	v_lshl_add_u64 v[230:231], s[58:59], 0, v[134:135]
	s_nop 0
	global_load_lds_dwordx4 v[226:227], off
	s_mov_b32 m0, s30
	s_nop 0
	global_load_lds_dwordx4 v[228:229], off
	s_mov_b32 m0, s31
	s_nop 0
	global_load_lds_dwordx4 v[230:231], off
	v_lshl_add_u64 v[230:231], s[58:59], 0, v[132:133]
	s_mov_b32 m0, s53
	s_nop 0
	global_load_lds_dwordx4 v[230:231], off
	ds_read_b128 v[176:179], v147 offset:32768
	ds_read_b128 v[180:183], v147 offset:33792
	ds_read_b128 v[184:187], v147 offset:34816
	ds_read_b128 v[200:203], v147 offset:35840
	ds_read_b128 v[204:207], v147 offset:36864
	ds_read_b128 v[208:211], v147 offset:37888
	ds_read_b128 v[212:215], v147 offset:38912
	ds_read_b128 v[216:219], v147 offset:39936
	s_waitcnt vmcnt(8)
	s_waitcnt lgkmcnt(0)
	s_barrier
	s_setprio 1
	s_waitcnt lgkmcnt(0)
	v_mfma_f32_16x16x32_bf16 v[122:125], v[140:143], v[176:179], v[122:125]
	v_mfma_f32_16x16x32_bf16 v[126:129], v[152:155], v[176:179], v[126:129]
	v_mfma_f32_16x16x32_bf16 v[110:113], v[140:143], v[184:187], v[110:113]
	v_mfma_f32_16x16x32_bf16 v[106:109], v[152:155], v[184:187], v[106:109]
	v_mfma_f32_16x16x32_bf16 v[94:97], v[140:143], v[204:207], v[94:97]
	v_mfma_f32_16x16x32_bf16 v[90:93], v[152:155], v[204:207], v[90:93]
	v_mfma_f32_16x16x32_bf16 v[78:81], v[140:143], v[212:215], v[78:81]
	v_mfma_f32_16x16x32_bf16 v[74:77], v[152:155], v[212:215], v[74:77]
	v_mfma_f32_16x16x32_bf16 v[122:125], v[148:151], v[180:183], v[122:125]
	v_mfma_f32_16x16x32_bf16 v[126:129], v[156:159], v[180:183], v[126:129]
	v_mfma_f32_16x16x32_bf16 v[110:113], v[148:151], v[200:203], v[110:113]
	v_mfma_f32_16x16x32_bf16 v[106:109], v[156:159], v[200:203], v[106:109]
	v_mfma_f32_16x16x32_bf16 v[94:97], v[148:151], v[208:211], v[94:97]
	v_mfma_f32_16x16x32_bf16 v[90:93], v[156:159], v[208:211], v[90:93]
	v_mfma_f32_16x16x32_bf16 v[78:81], v[148:151], v[216:219], v[78:81]
	v_mfma_f32_16x16x32_bf16 v[74:77], v[156:159], v[216:219], v[74:77]
	s_setprio 0
	s_setprio 1
	v_mfma_f32_16x16x32_bf16 v[118:121], v[160:163], v[176:179], v[118:121]
	v_mfma_f32_16x16x32_bf16 v[114:117], v[168:171], v[176:179], v[114:117]
	v_mfma_f32_16x16x32_bf16 v[102:105], v[160:163], v[184:187], v[102:105]
	v_mfma_f32_16x16x32_bf16 v[98:101], v[168:171], v[184:187], v[98:101]
	v_mfma_f32_16x16x32_bf16 v[86:89], v[160:163], v[204:207], v[86:89]
	v_mfma_f32_16x16x32_bf16 v[82:85], v[168:171], v[204:207], v[82:85]
	v_mfma_f32_16x16x32_bf16 v[70:73], v[160:163], v[212:215], v[70:73]
	v_mfma_f32_16x16x32_bf16 v[66:69], v[168:171], v[212:215], v[66:69]
	v_mfma_f32_16x16x32_bf16 v[118:121], v[164:167], v[180:183], v[118:121]
	v_mfma_f32_16x16x32_bf16 v[114:117], v[172:175], v[180:183], v[114:117]
	v_mfma_f32_16x16x32_bf16 v[102:105], v[164:167], v[200:203], v[102:105]
	v_mfma_f32_16x16x32_bf16 v[98:101], v[172:175], v[200:203], v[98:101]
	v_mfma_f32_16x16x32_bf16 v[86:89], v[164:167], v[208:211], v[86:89]
	v_mfma_f32_16x16x32_bf16 v[82:85], v[172:175], v[208:211], v[82:85]
	v_mfma_f32_16x16x32_bf16 v[70:73], v[164:167], v[216:219], v[70:73]
	v_mfma_f32_16x16x32_bf16 v[66:69], v[172:175], v[216:219], v[66:69]
	s_setprio 0
	s_barrier
	s_add_i32 s58, s75, s5
	v_lshl_add_u64 v[188:189], v[188:189], 0, s[24:25]
	s_mov_b32 m0, s58
	ds_read_b128 v[176:179], v147 offset:49152
	ds_read_b128 v[180:183], v147 offset:50176
	ds_read_b128 v[184:187], v147 offset:51200
	ds_read_b128 v[200:203], v147 offset:52224
	ds_read_b128 v[204:207], v147 offset:53248
	ds_read_b128 v[208:211], v147 offset:54272
	ds_read_b128 v[212:215], v147 offset:55296
	ds_read_b128 v[216:219], v147 offset:56320
	global_load_lds_dwordx4 v[188:189], off
	v_lshl_add_u64 v[188:189], v[220:221], 0, s[24:25]
	s_add_i32 m0, s58, 0x2000
	s_add_i32 s58, s78, s5
	global_load_lds_dwordx4 v[188:189], off
	v_lshl_add_u64 v[188:189], v[222:223], 0, s[24:25]
	s_mov_b32 m0, s58
	s_nop 0
	global_load_lds_dwordx4 v[188:189], off
	v_lshl_add_u64 v[188:189], v[224:225], 0, s[24:25]
	s_add_i32 m0, s58, 0x2000
	s_nop 0
	global_load_lds_dwordx4 v[188:189], off
	s_waitcnt vmcnt(6)
	s_waitcnt lgkmcnt(0)
	s_barrier
	s_setprio 1
	s_waitcnt lgkmcnt(0)
	v_mfma_f32_16x16x32_bf16 v[62:65], v[140:143], v[176:179], v[62:65]
	v_mfma_f32_16x16x32_bf16 v[58:61], v[152:155], v[176:179], v[58:61]
	v_mfma_f32_16x16x32_bf16 v[46:49], v[140:143], v[184:187], v[46:49]
	v_mfma_f32_16x16x32_bf16 v[42:45], v[152:155], v[184:187], v[42:45]
	v_mfma_f32_16x16x32_bf16 v[30:33], v[140:143], v[204:207], v[30:33]
	v_mfma_f32_16x16x32_bf16 v[26:29], v[152:155], v[204:207], v[26:29]
	v_mfma_f32_16x16x32_bf16 v[14:17], v[140:143], v[212:215], v[14:17]
	v_mfma_f32_16x16x32_bf16 v[10:13], v[152:155], v[212:215], v[10:13]
	v_mfma_f32_16x16x32_bf16 v[62:65], v[148:151], v[180:183], v[62:65]
	v_mfma_f32_16x16x32_bf16 v[58:61], v[156:159], v[180:183], v[58:61]
	v_mfma_f32_16x16x32_bf16 v[46:49], v[148:151], v[200:203], v[46:49]
	v_mfma_f32_16x16x32_bf16 v[42:45], v[156:159], v[200:203], v[42:45]
	v_mfma_f32_16x16x32_bf16 v[30:33], v[148:151], v[208:211], v[30:33]
	v_mfma_f32_16x16x32_bf16 v[26:29], v[156:159], v[208:211], v[26:29]
	v_mfma_f32_16x16x32_bf16 v[14:17], v[148:151], v[216:219], v[14:17]
	v_mfma_f32_16x16x32_bf16 v[10:13], v[156:159], v[216:219], v[10:13]
	s_setprio 0
	s_setprio 1
	v_mfma_f32_16x16x32_bf16 v[54:57], v[160:163], v[176:179], v[54:57]
	v_mfma_f32_16x16x32_bf16 v[50:53], v[168:171], v[176:179], v[50:53]
	v_mfma_f32_16x16x32_bf16 v[38:41], v[160:163], v[184:187], v[38:41]
	v_mfma_f32_16x16x32_bf16 v[34:37], v[168:171], v[184:187], v[34:37]
	v_mfma_f32_16x16x32_bf16 v[22:25], v[160:163], v[204:207], v[22:25]
	v_mfma_f32_16x16x32_bf16 v[18:21], v[168:171], v[204:207], v[18:21]
	v_mfma_f32_16x16x32_bf16 v[6:9], v[160:163], v[212:215], v[6:9]
	v_mfma_f32_16x16x32_bf16 v[2:5], v[168:171], v[212:215], v[2:5]
	v_mfma_f32_16x16x32_bf16 v[54:57], v[164:167], v[180:183], v[54:57]
	v_mfma_f32_16x16x32_bf16 v[50:53], v[172:175], v[180:183], v[50:53]
	v_mfma_f32_16x16x32_bf16 v[38:41], v[164:167], v[200:203], v[38:41]
	v_mfma_f32_16x16x32_bf16 v[34:37], v[172:175], v[200:203], v[34:37]
	v_mfma_f32_16x16x32_bf16 v[22:25], v[164:167], v[208:211], v[22:25]
	v_mfma_f32_16x16x32_bf16 v[18:21], v[172:175], v[208:211], v[18:21]
	v_mfma_f32_16x16x32_bf16 v[6:9], v[164:167], v[216:219], v[6:9]
	v_mfma_f32_16x16x32_bf16 v[2:5], v[172:175], v[216:219], v[2:5]
	s_setprio 0
	s_barrier
	s_add_u32 s56, s56, 0x100
	s_addc_u32 s57, s57, 0
	s_add_u32 s51, s51, 0x100
	s_addc_u32 s55, s55, 0
	s_cmp_ge_i32 s74, s61
	s_mov_b32 s58, s74
	s_cbranch_scc0 .LBB0_230
	v_readlane_b32 s74, v236, 30
	v_readlane_b32 s75, v236, 31
	s_mov_b32 s78, s76

.LBB0_266:
	s_add_i32 s60, s58, 2
	s_add_u32 s61, s56, 0x80
	s_addc_u32 s59, s57, 0
	s_add_i32 s64, 0, 0x10000
	s_cmp_eq_u32 s39, s58
	s_cselect_b32 s59, s29, s59
	s_cselect_b32 s58, s50, s61
	s_cselect_b32 s63, s45, s55
	s_cselect_b32 s62, s44, s51
	s_add_i32 s61, 0, 0x14000
	v_add_u32_e32 v152, s64, v201
	v_add_u32_e32 v168, s61, v201
	ds_read_b128 v[140:143], v152
	ds_read_b128 v[144:147], v152 offset:1024
	ds_read_b128 v[148:151], v152 offset:2048
	ds_read_b128 v[152:155], v152 offset:3072
	ds_read_b128 v[156:159], v168
	ds_read_b128 v[160:163], v168 offset:1024
	ds_read_b128 v[164:167], v168 offset:2048
	ds_read_b128 v[168:171], v168 offset:3072
	v_lshl_add_u64 v[188:189], s[56:57], 0, v[134:135]
	s_mov_b32 m0, s83
	s_nop 0
	global_load_lds_dwordx4 v[188:189], off
	v_lshl_add_u64 v[188:189], s[56:57], 0, v[132:133]
	s_mov_b32 m0, s38
	s_nop 0
	global_load_lds_dwordx4 v[188:189], off
	v_lshl_add_u64 v[188:189], s[56:57], 0, v[136:137]
	s_add_i32 m0, s30, 0xc000
	s_nop 0
	global_load_lds_dwordx4 v[188:189], off
	v_lshl_add_u64 v[188:189], s[56:57], 0, v[138:139]
	s_add_i32 m0, s30, 0xe000
	s_nop 0
	global_load_lds_dwordx4 v[188:189], off
	ds_read_b128 v[172:175], v202
	ds_read_b128 v[176:179], v202 offset:1024
	ds_read_b128 v[180:183], v202 offset:2048
	ds_read_b128 v[184:187], v202 offset:3072
	ds_read_b128 v[204:207], v202 offset:4096
	ds_read_b128 v[208:211], v202 offset:5120
	ds_read_b128 v[212:215], v202 offset:6144
	ds_read_b128 v[216:219], v202 offset:7168
	s_waitcnt vmcnt(8)
	s_waitcnt lgkmcnt(0)
	s_barrier
	s_setprio 1
	s_waitcnt lgkmcnt(0)
	v_mfma_f32_16x16x32_bf16 v[122:125], v[140:143], v[172:175], v[122:125]
	v_mfma_f32_16x16x32_bf16 v[126:129], v[148:151], v[172:175], v[126:129]
	v_mfma_f32_16x16x32_bf16 v[110:113], v[140:143], v[180:183], v[110:113]
	v_mfma_f32_16x16x32_bf16 v[106:109], v[148:151], v[180:183], v[106:109]
	v_mfma_f32_16x16x32_bf16 v[94:97], v[140:143], v[204:207], v[94:97]
	v_mfma_f32_16x16x32_bf16 v[90:93], v[148:151], v[204:207], v[90:93]
	v_mfma_f32_16x16x32_bf16 v[78:81], v[140:143], v[212:215], v[78:81]
	v_mfma_f32_16x16x32_bf16 v[74:77], v[148:151], v[212:215], v[74:77]
	v_mfma_f32_16x16x32_bf16 v[122:125], v[144:147], v[176:179], v[122:125]
	v_mfma_f32_16x16x32_bf16 v[126:129], v[152:155], v[176:179], v[126:129]
	v_mfma_f32_16x16x32_bf16 v[110:113], v[144:147], v[184:187], v[110:113]
	v_mfma_f32_16x16x32_bf16 v[106:109], v[152:155], v[184:187], v[106:109]
	v_mfma_f32_16x16x32_bf16 v[94:97], v[144:147], v[208:211], v[94:97]
	v_mfma_f32_16x16x32_bf16 v[90:93], v[152:155], v[208:211], v[90:93]
	v_mfma_f32_16x16x32_bf16 v[78:81], v[144:147], v[216:219], v[78:81]
	v_mfma_f32_16x16x32_bf16 v[74:77], v[152:155], v[216:219], v[74:77]
	s_setprio 0
	s_setprio 1
	v_mfma_f32_16x16x32_bf16 v[118:121], v[156:159], v[172:175], v[118:121]
	v_mfma_f32_16x16x32_bf16 v[114:117], v[164:167], v[172:175], v[114:117]
	v_mfma_f32_16x16x32_bf16 v[102:105], v[156:159], v[180:183], v[102:105]
	v_mfma_f32_16x16x32_bf16 v[98:101], v[164:167], v[180:183], v[98:101]
	v_mfma_f32_16x16x32_bf16 v[86:89], v[156:159], v[204:207], v[86:89]
	v_mfma_f32_16x16x32_bf16 v[82:85], v[164:167], v[204:207], v[82:85]
	v_mfma_f32_16x16x32_bf16 v[70:73], v[156:159], v[212:215], v[70:73]
	v_mfma_f32_16x16x32_bf16 v[66:69], v[164:167], v[212:215], v[66:69]
	v_mfma_f32_16x16x32_bf16 v[118:121], v[160:163], v[176:179], v[118:121]
	v_mfma_f32_16x16x32_bf16 v[114:117], v[168:171], v[176:179], v[114:117]
	v_mfma_f32_16x16x32_bf16 v[102:105], v[160:163], v[184:187], v[102:105]
	v_mfma_f32_16x16x32_bf16 v[98:101], v[168:171], v[184:187], v[98:101]
	v_mfma_f32_16x16x32_bf16 v[86:89], v[160:163], v[208:211], v[86:89]
	v_mfma_f32_16x16x32_bf16 v[82:85], v[168:171], v[208:211], v[82:85]
	v_mfma_f32_16x16x32_bf16 v[70:73], v[160:163], v[216:219], v[70:73]
	v_mfma_f32_16x16x32_bf16 v[66:69], v[168:171], v[216:219], v[66:69]
	s_setprio 0
	s_barrier
	s_add_i32 s64, s64, s27
	v_lshl_add_u64 v[188:189], s[62:63], 0, v[0:1]
	s_mov_b32 m0, s64
	ds_read_b128 v[172:175], v202 offset:16384
	ds_read_b128 v[176:179], v202 offset:17408
	ds_read_b128 v[180:183], v202 offset:18432
	ds_read_b128 v[184:187], v202 offset:19456
	ds_read_b128 v[204:207], v202 offset:20480
	ds_read_b128 v[208:211], v202 offset:21504
	ds_read_b128 v[212:215], v202 offset:22528
	ds_read_b128 v[216:219], v202 offset:23552
	global_load_lds_dwordx4 v[188:189], off
	s_add_i32 m0, s64, 0x2000
	v_lshl_add_u64 v[220:221], s[62:63], 0, v[130:131]
	s_add_u32 s62, s62, s6
	s_addc_u32 s63, s63, s7
	s_add_i32 s61, s61, s27
	global_load_lds_dwordx4 v[220:221], off
	v_lshl_add_u64 v[222:223], s[62:63], 0, v[0:1]
	s_mov_b32 m0, s61
	v_lshl_add_u64 v[224:225], s[62:63], 0, v[130:131]
	global_load_lds_dwordx4 v[222:223], off
	s_add_i32 m0, s61, 0x2000
	v_lshl_add_u64 v[226:227], s[58:59], 0, v[134:135]
	global_load_lds_dwordx4 v[224:225], off
	v_lshl_add_u64 v[228:229], s[58:59], 0, v[132:133]
	s_waitcnt vmcnt(6)
	s_waitcnt lgkmcnt(0)
	s_barrier
	s_setprio 1
	s_waitcnt lgkmcnt(0)
	v_mfma_f32_16x16x32_bf16 v[62:65], v[140:143], v[172:175], v[62:65]
	v_mfma_f32_16x16x32_bf16 v[58:61], v[148:151], v[172:175], v[58:61]
	v_mfma_f32_16x16x32_bf16 v[46:49], v[140:143], v[180:183], v[46:49]
	v_mfma_f32_16x16x32_bf16 v[42:45], v[148:151], v[180:183], v[42:45]
	v_mfma_f32_16x16x32_bf16 v[30:33], v[140:143], v[204:207], v[30:33]
	v_mfma_f32_16x16x32_bf16 v[26:29], v[148:151], v[204:207], v[26:29]
	v_mfma_f32_16x16x32_bf16 v[14:17], v[140:143], v[212:215], v[14:17]
	v_mfma_f32_16x16x32_bf16 v[10:13], v[148:151], v[212:215], v[10:13]
	v_mfma_f32_16x16x32_bf16 v[62:65], v[144:147], v[176:179], v[62:65]
	v_mfma_f32_16x16x32_bf16 v[58:61], v[152:155], v[176:179], v[58:61]
	v_mfma_f32_16x16x32_bf16 v[46:49], v[144:147], v[184:187], v[46:49]
	v_mfma_f32_16x16x32_bf16 v[42:45], v[152:155], v[184:187], v[42:45]
	v_mfma_f32_16x16x32_bf16 v[30:33], v[144:147], v[208:211], v[30:33]
	v_mfma_f32_16x16x32_bf16 v[26:29], v[152:155], v[208:211], v[26:29]
	v_mfma_f32_16x16x32_bf16 v[14:17], v[144:147], v[216:219], v[14:17]
	v_mfma_f32_16x16x32_bf16 v[10:13], v[152:155], v[216:219], v[10:13]
	s_setprio 0
	s_setprio 1
	v_mfma_f32_16x16x32_bf16 v[54:57], v[156:159], v[172:175], v[54:57]
	v_mfma_f32_16x16x32_bf16 v[50:53], v[164:167], v[172:175], v[50:53]
	v_mfma_f32_16x16x32_bf16 v[38:41], v[156:159], v[180:183], v[38:41]
	v_mfma_f32_16x16x32_bf16 v[34:37], v[164:167], v[180:183], v[34:37]
	v_mfma_f32_16x16x32_bf16 v[22:25], v[156:159], v[204:207], v[22:25]
	v_mfma_f32_16x16x32_bf16 v[18:21], v[164:167], v[204:207], v[18:21]
	v_mfma_f32_16x16x32_bf16 v[6:9], v[156:159], v[212:215], v[6:9]
	v_mfma_f32_16x16x32_bf16 v[2:5], v[164:167], v[212:215], v[2:5]
	v_mfma_f32_16x16x32_bf16 v[54:57], v[160:163], v[176:179], v[54:57]
	v_mfma_f32_16x16x32_bf16 v[50:53], v[168:171], v[176:179], v[50:53]
	v_mfma_f32_16x16x32_bf16 v[38:41], v[160:163], v[184:187], v[38:41]
	v_mfma_f32_16x16x32_bf16 v[34:37], v[168:171], v[184:187], v[34:37]
	v_mfma_f32_16x16x32_bf16 v[22:25], v[160:163], v[208:211], v[22:25]
	v_mfma_f32_16x16x32_bf16 v[18:21], v[168:171], v[208:211], v[18:21]
	v_mfma_f32_16x16x32_bf16 v[6:9], v[160:163], v[216:219], v[6:9]
	v_mfma_f32_16x16x32_bf16 v[2:5], v[168:171], v[216:219], v[2:5]
	s_setprio 0
	s_barrier
	s_add_i32 s61, 0, 0x18000
	s_add_i32 s62, 0, 0x1c000
	v_add_u32_e32 v152, s61, v201
	v_add_u32_e32 v168, s62, v201
	ds_read_b128 v[140:143], v152
	ds_read_b128 v[144:147], v152 offset:1024
	ds_read_b128 v[148:151], v152 offset:2048
	ds_read_b128 v[152:155], v152 offset:3072
	ds_read_b128 v[156:159], v168
	ds_read_b128 v[160:163], v168 offset:1024
	ds_read_b128 v[164:167], v168 offset:2048
	ds_read_b128 v[168:171], v168 offset:3072
	s_add_u32 s58, s58, s2
	s_addc_u32 s59, s59, s3
	s_mov_b32 m0, s30
	v_lshl_add_u64 v[230:231], s[58:59], 0, v[134:135]
	s_nop 0
	global_load_lds_dwordx4 v[226:227], off
	s_mov_b32 m0, s31
	s_nop 0
	global_load_lds_dwordx4 v[228:229], off
	s_mov_b32 m0, s53
	s_nop 0
	global_load_lds_dwordx4 v[230:231], off
	v_lshl_add_u64 v[230:231], s[58:59], 0, v[132:133]
	s_mov_b32 m0, s72
	s_nop 0
	global_load_lds_dwordx4 v[230:231], off
	ds_read_b128 v[172:175], v202 offset:32768
	ds_read_b128 v[176:179], v202 offset:33792
	ds_read_b128 v[180:183], v202 offset:34816
	ds_read_b128 v[184:187], v202 offset:35840
	ds_read_b128 v[204:207], v202 offset:36864
	ds_read_b128 v[208:211], v202 offset:37888
	ds_read_b128 v[212:215], v202 offset:38912
	ds_read_b128 v[216:219], v202 offset:39936
	s_waitcnt vmcnt(8)
	s_waitcnt lgkmcnt(0)
	s_barrier
	s_setprio 1
	s_waitcnt lgkmcnt(0)
	v_mfma_f32_16x16x32_bf16 v[122:125], v[140:143], v[172:175], v[122:125]
	v_mfma_f32_16x16x32_bf16 v[126:129], v[148:151], v[172:175], v[126:129]
	v_mfma_f32_16x16x32_bf16 v[110:113], v[140:143], v[180:183], v[110:113]
	v_mfma_f32_16x16x32_bf16 v[106:109], v[148:151], v[180:183], v[106:109]
	v_mfma_f32_16x16x32_bf16 v[94:97], v[140:143], v[204:207], v[94:97]
	v_mfma_f32_16x16x32_bf16 v[90:93], v[148:151], v[204:207], v[90:93]
	v_mfma_f32_16x16x32_bf16 v[78:81], v[140:143], v[212:215], v[78:81]
	v_mfma_f32_16x16x32_bf16 v[74:77], v[148:151], v[212:215], v[74:77]
	v_mfma_f32_16x16x32_bf16 v[122:125], v[144:147], v[176:179], v[122:125]
	v_mfma_f32_16x16x32_bf16 v[126:129], v[152:155], v[176:179], v[126:129]
	v_mfma_f32_16x16x32_bf16 v[110:113], v[144:147], v[184:187], v[110:113]
	v_mfma_f32_16x16x32_bf16 v[106:109], v[152:155], v[184:187], v[106:109]
	v_mfma_f32_16x16x32_bf16 v[94:97], v[144:147], v[208:211], v[94:97]
	v_mfma_f32_16x16x32_bf16 v[90:93], v[152:155], v[208:211], v[90:93]
	v_mfma_f32_16x16x32_bf16 v[78:81], v[144:147], v[216:219], v[78:81]
	v_mfma_f32_16x16x32_bf16 v[74:77], v[152:155], v[216:219], v[74:77]
	s_setprio 0
	s_setprio 1
	v_mfma_f32_16x16x32_bf16 v[118:121], v[156:159], v[172:175], v[118:121]
	v_mfma_f32_16x16x32_bf16 v[114:117], v[164:167], v[172:175], v[114:117]
	v_mfma_f32_16x16x32_bf16 v[102:105], v[156:159], v[180:183], v[102:105]
	v_mfma_f32_16x16x32_bf16 v[98:101], v[164:167], v[180:183], v[98:101]
	v_mfma_f32_16x16x32_bf16 v[86:89], v[156:159], v[204:207], v[86:89]
	v_mfma_f32_16x16x32_bf16 v[82:85], v[164:167], v[204:207], v[82:85]
	v_mfma_f32_16x16x32_bf16 v[70:73], v[156:159], v[212:215], v[70:73]
	v_mfma_f32_16x16x32_bf16 v[66:69], v[164:167], v[212:215], v[66:69]
	v_mfma_f32_16x16x32_bf16 v[118:121], v[160:163], v[176:179], v[118:121]
	v_mfma_f32_16x16x32_bf16 v[114:117], v[168:171], v[176:179], v[114:117]
	v_mfma_f32_16x16x32_bf16 v[102:105], v[160:163], v[184:187], v[102:105]
	v_mfma_f32_16x16x32_bf16 v[98:101], v[168:171], v[184:187], v[98:101]
	v_mfma_f32_16x16x32_bf16 v[86:89], v[160:163], v[208:211], v[86:89]
	v_mfma_f32_16x16x32_bf16 v[82:85], v[168:171], v[208:211], v[82:85]
	v_mfma_f32_16x16x32_bf16 v[70:73], v[160:163], v[216:219], v[70:73]
	v_mfma_f32_16x16x32_bf16 v[66:69], v[168:171], v[216:219], v[66:69]
	s_setprio 0
	s_barrier
	s_add_i32 s58, s61, s27
	v_lshl_add_u64 v[188:189], v[188:189], 0, s[24:25]
	s_mov_b32 m0, s58
	ds_read_b128 v[172:175], v202 offset:49152
	ds_read_b128 v[176:179], v202 offset:50176
	ds_read_b128 v[180:183], v202 offset:51200
	ds_read_b128 v[184:187], v202 offset:52224
	ds_read_b128 v[204:207], v202 offset:53248
	ds_read_b128 v[208:211], v202 offset:54272
	ds_read_b128 v[212:215], v202 offset:55296
	ds_read_b128 v[216:219], v202 offset:56320
	global_load_lds_dwordx4 v[188:189], off
	v_lshl_add_u64 v[188:189], v[220:221], 0, s[24:25]
	s_add_i32 m0, s58, 0x2000
	s_add_i32 s58, s62, s27
	global_load_lds_dwordx4 v[188:189], off
	v_lshl_add_u64 v[188:189], v[222:223], 0, s[24:25]
	s_mov_b32 m0, s58
	s_nop 0
	global_load_lds_dwordx4 v[188:189], off
	v_lshl_add_u64 v[188:189], v[224:225], 0, s[24:25]
	s_add_i32 m0, s58, 0x2000
	s_nop 0
	global_load_lds_dwordx4 v[188:189], off
	s_waitcnt vmcnt(6)
	s_waitcnt lgkmcnt(0)
	s_barrier
	s_setprio 1
	s_waitcnt lgkmcnt(0)
	v_mfma_f32_16x16x32_bf16 v[62:65], v[140:143], v[172:175], v[62:65]
	v_mfma_f32_16x16x32_bf16 v[58:61], v[148:151], v[172:175], v[58:61]
	v_mfma_f32_16x16x32_bf16 v[46:49], v[140:143], v[180:183], v[46:49]
	v_mfma_f32_16x16x32_bf16 v[42:45], v[148:151], v[180:183], v[42:45]
	v_mfma_f32_16x16x32_bf16 v[30:33], v[140:143], v[204:207], v[30:33]
	v_mfma_f32_16x16x32_bf16 v[26:29], v[148:151], v[204:207], v[26:29]
	v_mfma_f32_16x16x32_bf16 v[14:17], v[140:143], v[212:215], v[14:17]
	v_mfma_f32_16x16x32_bf16 v[10:13], v[148:151], v[212:215], v[10:13]
	v_mfma_f32_16x16x32_bf16 v[62:65], v[144:147], v[176:179], v[62:65]
	v_mfma_f32_16x16x32_bf16 v[58:61], v[152:155], v[176:179], v[58:61]
	v_mfma_f32_16x16x32_bf16 v[46:49], v[144:147], v[184:187], v[46:49]
	v_mfma_f32_16x16x32_bf16 v[42:45], v[152:155], v[184:187], v[42:45]
	v_mfma_f32_16x16x32_bf16 v[30:33], v[144:147], v[208:211], v[30:33]
	v_mfma_f32_16x16x32_bf16 v[26:29], v[152:155], v[208:211], v[26:29]
	v_mfma_f32_16x16x32_bf16 v[14:17], v[144:147], v[216:219], v[14:17]
	v_mfma_f32_16x16x32_bf16 v[10:13], v[152:155], v[216:219], v[10:13]
	s_setprio 0
	s_setprio 1
	v_mfma_f32_16x16x32_bf16 v[54:57], v[156:159], v[172:175], v[54:57]
	v_mfma_f32_16x16x32_bf16 v[50:53], v[164:167], v[172:175], v[50:53]
	v_mfma_f32_16x16x32_bf16 v[38:41], v[156:159], v[180:183], v[38:41]
	v_mfma_f32_16x16x32_bf16 v[34:37], v[164:167], v[180:183], v[34:37]
	v_mfma_f32_16x16x32_bf16 v[22:25], v[156:159], v[204:207], v[22:25]
	v_mfma_f32_16x16x32_bf16 v[18:21], v[164:167], v[204:207], v[18:21]
	v_mfma_f32_16x16x32_bf16 v[6:9], v[156:159], v[212:215], v[6:9]
	v_mfma_f32_16x16x32_bf16 v[2:5], v[164:167], v[212:215], v[2:5]
	v_mfma_f32_16x16x32_bf16 v[54:57], v[160:163], v[176:179], v[54:57]
	v_mfma_f32_16x16x32_bf16 v[50:53], v[168:171], v[176:179], v[50:53]
	v_mfma_f32_16x16x32_bf16 v[38:41], v[160:163], v[184:187], v[38:41]
	v_mfma_f32_16x16x32_bf16 v[34:37], v[168:171], v[184:187], v[34:37]
	v_mfma_f32_16x16x32_bf16 v[22:25], v[160:163], v[208:211], v[22:25]
	v_mfma_f32_16x16x32_bf16 v[18:21], v[168:171], v[208:211], v[18:21]
	v_mfma_f32_16x16x32_bf16 v[6:9], v[160:163], v[216:219], v[6:9]
	v_mfma_f32_16x16x32_bf16 v[2:5], v[168:171], v[216:219], v[2:5]
	s_setprio 0
	s_barrier
	s_add_u32 s56, s56, 0x100
	s_addc_u32 s57, s57, 0
	s_add_u32 s51, s51, 0x100
	s_addc_u32 s55, s55, 0
	s_cmp_ge_i32 s60, s74
	s_mov_b32 s58, s60
	s_cbranch_scc0 .LBB0_266

.LBB0_467:
	s_add_i32 s46, s42, 2
	s_add_u32 s47, s40, 0x80
	s_addc_u32 s43, s41, 0
	s_add_i32 s50, 0, 0x10000
	s_cmp_eq_u32 s75, s42
	s_cselect_b32 s43, s28, s43
	s_cselect_b32 s42, s29, s47
	v_add_u32_e32 v0, s50, v180
	s_cselect_b32 s49, s81, s45
	s_cselect_b32 s48, s80, s44
	s_add_i32 s47, 0, 0x14000
	ds_read_b128 v[130:133], v0
	ds_read_b128 v[134:137], v0 offset:1024
	ds_read_b128 v[138:141], v0 offset:2048
	ds_read_b128 v[142:145], v0 offset:3072
	v_add_u32_e32 v0, s47, v180
	ds_read_b128 v[158:161], v0
	ds_read_b128 v[162:165], v0 offset:1024
	ds_read_b128 v[166:169], v0 offset:2048
	ds_read_b128 v[170:173], v0 offset:3072
	v_lshl_add_u64 v[220:221], s[40:41], 0, v[152:153]
	s_mov_b32 m0, s27
	s_nop 0
	global_load_lds_dwordx4 v[220:221], off
	v_lshl_add_u64 v[220:221], s[40:41], 0, v[148:149]
	s_mov_b32 m0, s72
	s_nop 0
	global_load_lds_dwordx4 v[220:221], off
	v_lshl_add_u64 v[220:221], s[40:41], 0, v[154:155]
	s_add_i32 m0, s53, 0xc000
	s_nop 0
	global_load_lds_dwordx4 v[220:221], off
	v_lshl_add_u64 v[220:221], s[40:41], 0, v[156:157]
	s_add_i32 m0, s53, 0xe000
	s_nop 0
	global_load_lds_dwordx4 v[220:221], off
	ds_read_b128 v[174:177], v181
	ds_read_b128 v[182:185], v181 offset:1024
	ds_read_b128 v[186:189], v181 offset:2048
	ds_read_b128 v[200:203], v181 offset:3072
	ds_read_b128 v[204:207], v181 offset:4096
	ds_read_b128 v[208:211], v181 offset:5120
	ds_read_b128 v[212:215], v181 offset:6144
	ds_read_b128 v[216:219], v181 offset:7168
	s_waitcnt vmcnt(8)
	s_waitcnt lgkmcnt(0)
	s_barrier
	s_setprio 1
	s_waitcnt lgkmcnt(0)
	v_mfma_f32_16x16x32_bf16 v[126:129], v[130:133], v[174:177], v[126:129]
	v_mfma_f32_16x16x32_bf16 v[122:125], v[138:141], v[174:177], v[122:125]
	v_mfma_f32_16x16x32_bf16 v[110:113], v[130:133], v[186:189], v[110:113]
	v_mfma_f32_16x16x32_bf16 v[106:109], v[138:141], v[186:189], v[106:109]
	v_mfma_f32_16x16x32_bf16 v[94:97], v[130:133], v[204:207], v[94:97]
	v_mfma_f32_16x16x32_bf16 v[90:93], v[138:141], v[204:207], v[90:93]
	v_mfma_f32_16x16x32_bf16 v[78:81], v[130:133], v[212:215], v[78:81]
	v_mfma_f32_16x16x32_bf16 v[74:77], v[138:141], v[212:215], v[74:77]
	v_mfma_f32_16x16x32_bf16 v[126:129], v[134:137], v[182:185], v[126:129]
	v_mfma_f32_16x16x32_bf16 v[122:125], v[142:145], v[182:185], v[122:125]
	v_mfma_f32_16x16x32_bf16 v[110:113], v[134:137], v[200:203], v[110:113]
	v_mfma_f32_16x16x32_bf16 v[106:109], v[142:145], v[200:203], v[106:109]
	v_mfma_f32_16x16x32_bf16 v[94:97], v[134:137], v[208:211], v[94:97]
	v_mfma_f32_16x16x32_bf16 v[90:93], v[142:145], v[208:211], v[90:93]
	v_mfma_f32_16x16x32_bf16 v[78:81], v[134:137], v[216:219], v[78:81]
	v_mfma_f32_16x16x32_bf16 v[74:77], v[142:145], v[216:219], v[74:77]
	s_setprio 0
	s_setprio 1
	v_mfma_f32_16x16x32_bf16 v[118:121], v[158:161], v[174:177], v[118:121]
	v_mfma_f32_16x16x32_bf16 v[114:117], v[166:169], v[174:177], v[114:117]
	v_mfma_f32_16x16x32_bf16 v[102:105], v[158:161], v[186:189], v[102:105]
	v_mfma_f32_16x16x32_bf16 v[98:101], v[166:169], v[186:189], v[98:101]
	v_mfma_f32_16x16x32_bf16 v[86:89], v[158:161], v[204:207], v[86:89]
	v_mfma_f32_16x16x32_bf16 v[82:85], v[166:169], v[204:207], v[82:85]
	v_mfma_f32_16x16x32_bf16 v[70:73], v[158:161], v[212:215], v[70:73]
	v_mfma_f32_16x16x32_bf16 v[66:69], v[166:169], v[212:215], v[66:69]
	v_mfma_f32_16x16x32_bf16 v[118:121], v[162:165], v[182:185], v[118:121]
	v_mfma_f32_16x16x32_bf16 v[114:117], v[170:173], v[182:185], v[114:117]
	v_mfma_f32_16x16x32_bf16 v[102:105], v[162:165], v[200:203], v[102:105]
	v_mfma_f32_16x16x32_bf16 v[98:101], v[170:173], v[200:203], v[98:101]
	v_mfma_f32_16x16x32_bf16 v[86:89], v[162:165], v[208:211], v[86:89]
	v_mfma_f32_16x16x32_bf16 v[82:85], v[170:173], v[208:211], v[82:85]
	v_mfma_f32_16x16x32_bf16 v[70:73], v[162:165], v[216:219], v[70:73]
	v_mfma_f32_16x16x32_bf16 v[66:69], v[170:173], v[216:219], v[66:69]
	s_setprio 0
	s_barrier
	s_add_i32 s50, s50, s31
	v_lshl_add_u64 v[220:221], s[48:49], 0, v[150:151]
	s_mov_b32 m0, s50
	ds_read_b128 v[174:177], v181 offset:16384
	ds_read_b128 v[182:185], v181 offset:17408
	ds_read_b128 v[186:189], v181 offset:18432
	ds_read_b128 v[200:203], v181 offset:19456
	ds_read_b128 v[204:207], v181 offset:20480
	ds_read_b128 v[208:211], v181 offset:21504
	ds_read_b128 v[212:215], v181 offset:22528
	ds_read_b128 v[216:219], v181 offset:23552
	global_load_lds_dwordx4 v[220:221], off
	s_add_i32 m0, s50, 0x2000
	v_lshl_add_u64 v[222:223], s[48:49], 0, v[146:147]
	s_add_u32 s48, s48, s56
	s_addc_u32 s49, s49, s57
	s_add_i32 s47, s47, s31
	global_load_lds_dwordx4 v[222:223], off
	v_lshl_add_u64 v[224:225], s[48:49], 0, v[150:151]
	s_mov_b32 m0, s47
	v_lshl_add_u64 v[226:227], s[48:49], 0, v[146:147]
	global_load_lds_dwordx4 v[224:225], off
	s_add_i32 m0, s47, 0x2000
	v_lshl_add_u64 v[228:229], s[42:43], 0, v[152:153]
	global_load_lds_dwordx4 v[226:227], off
	v_lshl_add_u64 v[230:231], s[42:43], 0, v[148:149]
	s_waitcnt vmcnt(6)
	s_waitcnt lgkmcnt(0)
	s_barrier
	s_setprio 1
	s_waitcnt lgkmcnt(0)
	v_mfma_f32_16x16x32_bf16 v[62:65], v[130:133], v[174:177], v[62:65]
	v_mfma_f32_16x16x32_bf16 v[58:61], v[138:141], v[174:177], v[58:61]
	v_mfma_f32_16x16x32_bf16 v[46:49], v[130:133], v[186:189], v[46:49]
	v_mfma_f32_16x16x32_bf16 v[42:45], v[138:141], v[186:189], v[42:45]
	v_mfma_f32_16x16x32_bf16 v[30:33], v[130:133], v[204:207], v[30:33]
	v_mfma_f32_16x16x32_bf16 v[26:29], v[138:141], v[204:207], v[26:29]
	v_mfma_f32_16x16x32_bf16 v[14:17], v[130:133], v[212:215], v[14:17]
	v_mfma_f32_16x16x32_bf16 v[10:13], v[138:141], v[212:215], v[10:13]
	v_mfma_f32_16x16x32_bf16 v[62:65], v[134:137], v[182:185], v[62:65]
	v_mfma_f32_16x16x32_bf16 v[58:61], v[142:145], v[182:185], v[58:61]
	v_mfma_f32_16x16x32_bf16 v[46:49], v[134:137], v[200:203], v[46:49]
	v_mfma_f32_16x16x32_bf16 v[42:45], v[142:145], v[200:203], v[42:45]
	v_mfma_f32_16x16x32_bf16 v[30:33], v[134:137], v[208:211], v[30:33]
	v_mfma_f32_16x16x32_bf16 v[26:29], v[142:145], v[208:211], v[26:29]
	v_mfma_f32_16x16x32_bf16 v[14:17], v[134:137], v[216:219], v[14:17]
	v_mfma_f32_16x16x32_bf16 v[10:13], v[142:145], v[216:219], v[10:13]
	s_setprio 0
	s_setprio 1
	v_mfma_f32_16x16x32_bf16 v[54:57], v[158:161], v[174:177], v[54:57]
	v_mfma_f32_16x16x32_bf16 v[50:53], v[166:169], v[174:177], v[50:53]
	v_mfma_f32_16x16x32_bf16 v[38:41], v[158:161], v[186:189], v[38:41]
	v_mfma_f32_16x16x32_bf16 v[34:37], v[166:169], v[186:189], v[34:37]
	v_mfma_f32_16x16x32_bf16 v[22:25], v[158:161], v[204:207], v[22:25]
	v_mfma_f32_16x16x32_bf16 v[18:21], v[166:169], v[204:207], v[18:21]
	v_mfma_f32_16x16x32_bf16 v[6:9], v[158:161], v[212:215], v[6:9]
	v_mfma_f32_16x16x32_bf16 v[2:5], v[166:169], v[212:215], v[2:5]
	v_mfma_f32_16x16x32_bf16 v[54:57], v[162:165], v[182:185], v[54:57]
	v_mfma_f32_16x16x32_bf16 v[50:53], v[170:173], v[182:185], v[50:53]
	v_mfma_f32_16x16x32_bf16 v[38:41], v[162:165], v[200:203], v[38:41]
	v_mfma_f32_16x16x32_bf16 v[34:37], v[170:173], v[200:203], v[34:37]
	v_mfma_f32_16x16x32_bf16 v[22:25], v[162:165], v[208:211], v[22:25]
	v_mfma_f32_16x16x32_bf16 v[18:21], v[170:173], v[208:211], v[18:21]
	v_mfma_f32_16x16x32_bf16 v[6:9], v[162:165], v[216:219], v[6:9]
	v_mfma_f32_16x16x32_bf16 v[2:5], v[170:173], v[216:219], v[2:5]
	s_setprio 0
	s_barrier
	s_add_i32 s47, 0, 0x18000
	v_add_u32_e32 v0, s47, v180
	s_add_i32 s48, 0, 0x1c000
	ds_read_b128 v[130:133], v0
	ds_read_b128 v[134:137], v0 offset:1024
	ds_read_b128 v[138:141], v0 offset:2048
	ds_read_b128 v[142:145], v0 offset:3072
	v_add_u32_e32 v0, s48, v180
	ds_read_b128 v[158:161], v0
	ds_read_b128 v[162:165], v0 offset:1024
	ds_read_b128 v[166:169], v0 offset:2048
	ds_read_b128 v[170:173], v0 offset:3072
	s_add_u32 s42, s42, s54
	s_addc_u32 s43, s43, s55
	s_mov_b32 m0, s53
	v_lshl_add_u64 v[232:233], s[42:43], 0, v[152:153]
	s_nop 0
	global_load_lds_dwordx4 v[228:229], off
	s_mov_b32 m0, s4
	s_nop 0
	global_load_lds_dwordx4 v[230:231], off
	s_mov_b32 m0, s82
	s_nop 0
	global_load_lds_dwordx4 v[232:233], off
	v_lshl_add_u64 v[232:233], s[42:43], 0, v[148:149]
	s_mov_b32 m0, s83
	s_nop 0
	global_load_lds_dwordx4 v[232:233], off
	ds_read_b128 v[174:177], v181 offset:32768
	ds_read_b128 v[182:185], v181 offset:33792
	ds_read_b128 v[186:189], v181 offset:34816
	ds_read_b128 v[200:203], v181 offset:35840
	ds_read_b128 v[204:207], v181 offset:36864
	ds_read_b128 v[208:211], v181 offset:37888
	ds_read_b128 v[212:215], v181 offset:38912
	ds_read_b128 v[216:219], v181 offset:39936
	s_waitcnt vmcnt(8)
	s_waitcnt lgkmcnt(0)
	s_barrier
	s_setprio 1
	s_waitcnt lgkmcnt(0)
	v_mfma_f32_16x16x32_bf16 v[126:129], v[130:133], v[174:177], v[126:129]
	v_mfma_f32_16x16x32_bf16 v[122:125], v[138:141], v[174:177], v[122:125]
	v_mfma_f32_16x16x32_bf16 v[110:113], v[130:133], v[186:189], v[110:113]
	v_mfma_f32_16x16x32_bf16 v[106:109], v[138:141], v[186:189], v[106:109]
	v_mfma_f32_16x16x32_bf16 v[94:97], v[130:133], v[204:207], v[94:97]
	v_mfma_f32_16x16x32_bf16 v[90:93], v[138:141], v[204:207], v[90:93]
	v_mfma_f32_16x16x32_bf16 v[78:81], v[130:133], v[212:215], v[78:81]
	v_mfma_f32_16x16x32_bf16 v[74:77], v[138:141], v[212:215], v[74:77]
	v_mfma_f32_16x16x32_bf16 v[126:129], v[134:137], v[182:185], v[126:129]
	v_mfma_f32_16x16x32_bf16 v[122:125], v[142:145], v[182:185], v[122:125]
	v_mfma_f32_16x16x32_bf16 v[110:113], v[134:137], v[200:203], v[110:113]
	v_mfma_f32_16x16x32_bf16 v[106:109], v[142:145], v[200:203], v[106:109]
	v_mfma_f32_16x16x32_bf16 v[94:97], v[134:137], v[208:211], v[94:97]
	v_mfma_f32_16x16x32_bf16 v[90:93], v[142:145], v[208:211], v[90:93]
	v_mfma_f32_16x16x32_bf16 v[78:81], v[134:137], v[216:219], v[78:81]
	v_mfma_f32_16x16x32_bf16 v[74:77], v[142:145], v[216:219], v[74:77]
	s_setprio 0
	s_setprio 1
	v_mfma_f32_16x16x32_bf16 v[118:121], v[158:161], v[174:177], v[118:121]
	v_mfma_f32_16x16x32_bf16 v[114:117], v[166:169], v[174:177], v[114:117]
	v_mfma_f32_16x16x32_bf16 v[102:105], v[158:161], v[186:189], v[102:105]
	v_mfma_f32_16x16x32_bf16 v[98:101], v[166:169], v[186:189], v[98:101]
	v_mfma_f32_16x16x32_bf16 v[86:89], v[158:161], v[204:207], v[86:89]
	v_mfma_f32_16x16x32_bf16 v[82:85], v[166:169], v[204:207], v[82:85]
	v_mfma_f32_16x16x32_bf16 v[70:73], v[158:161], v[212:215], v[70:73]
	v_mfma_f32_16x16x32_bf16 v[66:69], v[166:169], v[212:215], v[66:69]
	v_mfma_f32_16x16x32_bf16 v[118:121], v[162:165], v[182:185], v[118:121]
	v_mfma_f32_16x16x32_bf16 v[114:117], v[170:173], v[182:185], v[114:117]
	v_mfma_f32_16x16x32_bf16 v[102:105], v[162:165], v[200:203], v[102:105]
	v_mfma_f32_16x16x32_bf16 v[98:101], v[170:173], v[200:203], v[98:101]
	v_mfma_f32_16x16x32_bf16 v[86:89], v[162:165], v[208:211], v[86:89]
	v_mfma_f32_16x16x32_bf16 v[82:85], v[170:173], v[208:211], v[82:85]
	v_mfma_f32_16x16x32_bf16 v[70:73], v[162:165], v[216:219], v[70:73]
	v_mfma_f32_16x16x32_bf16 v[66:69], v[170:173], v[216:219], v[66:69]
	s_setprio 0
	s_barrier
	s_add_i32 s42, s47, s31
	v_lshl_add_u64 v[220:221], v[220:221], 0, s[24:25]
	s_mov_b32 m0, s42
	ds_read_b128 v[174:177], v181 offset:49152
	ds_read_b128 v[182:185], v181 offset:50176
	ds_read_b128 v[186:189], v181 offset:51200
	ds_read_b128 v[200:203], v181 offset:52224
	ds_read_b128 v[204:207], v181 offset:53248
	ds_read_b128 v[208:211], v181 offset:54272
	ds_read_b128 v[212:215], v181 offset:55296
	ds_read_b128 v[216:219], v181 offset:56320
	global_load_lds_dwordx4 v[220:221], off
	v_lshl_add_u64 v[220:221], v[222:223], 0, s[24:25]
	s_add_i32 m0, s42, 0x2000
	s_add_i32 s42, s48, s31
	global_load_lds_dwordx4 v[220:221], off
	v_lshl_add_u64 v[220:221], v[224:225], 0, s[24:25]
	s_mov_b32 m0, s42
	s_nop 0
	global_load_lds_dwordx4 v[220:221], off
	v_lshl_add_u64 v[220:221], v[226:227], 0, s[24:25]
	s_add_i32 m0, s42, 0x2000
	s_nop 0
	global_load_lds_dwordx4 v[220:221], off
	s_waitcnt vmcnt(6)
	s_waitcnt lgkmcnt(0)
	s_barrier
	s_setprio 1
	s_waitcnt lgkmcnt(0)
	v_mfma_f32_16x16x32_bf16 v[62:65], v[130:133], v[174:177], v[62:65]
	v_mfma_f32_16x16x32_bf16 v[58:61], v[138:141], v[174:177], v[58:61]
	v_mfma_f32_16x16x32_bf16 v[46:49], v[130:133], v[186:189], v[46:49]
	v_mfma_f32_16x16x32_bf16 v[42:45], v[138:141], v[186:189], v[42:45]
	v_mfma_f32_16x16x32_bf16 v[30:33], v[130:133], v[204:207], v[30:33]
	v_mfma_f32_16x16x32_bf16 v[26:29], v[138:141], v[204:207], v[26:29]
	v_mfma_f32_16x16x32_bf16 v[14:17], v[130:133], v[212:215], v[14:17]
	v_mfma_f32_16x16x32_bf16 v[10:13], v[138:141], v[212:215], v[10:13]
	v_mfma_f32_16x16x32_bf16 v[62:65], v[134:137], v[182:185], v[62:65]
	v_mfma_f32_16x16x32_bf16 v[58:61], v[142:145], v[182:185], v[58:61]
	v_mfma_f32_16x16x32_bf16 v[46:49], v[134:137], v[200:203], v[46:49]
	v_mfma_f32_16x16x32_bf16 v[42:45], v[142:145], v[200:203], v[42:45]
	v_mfma_f32_16x16x32_bf16 v[30:33], v[134:137], v[208:211], v[30:33]
	v_mfma_f32_16x16x32_bf16 v[26:29], v[142:145], v[208:211], v[26:29]
	v_mfma_f32_16x16x32_bf16 v[14:17], v[134:137], v[216:219], v[14:17]
	v_mfma_f32_16x16x32_bf16 v[10:13], v[142:145], v[216:219], v[10:13]
	s_setprio 0
	s_setprio 1
	v_mfma_f32_16x16x32_bf16 v[54:57], v[158:161], v[174:177], v[54:57]
	v_mfma_f32_16x16x32_bf16 v[50:53], v[166:169], v[174:177], v[50:53]
	v_mfma_f32_16x16x32_bf16 v[38:41], v[158:161], v[186:189], v[38:41]
	v_mfma_f32_16x16x32_bf16 v[34:37], v[166:169], v[186:189], v[34:37]
	v_mfma_f32_16x16x32_bf16 v[22:25], v[158:161], v[204:207], v[22:25]
	v_mfma_f32_16x16x32_bf16 v[18:21], v[166:169], v[204:207], v[18:21]
	v_mfma_f32_16x16x32_bf16 v[6:9], v[158:161], v[212:215], v[6:9]
	v_mfma_f32_16x16x32_bf16 v[2:5], v[166:169], v[212:215], v[2:5]
	v_mfma_f32_16x16x32_bf16 v[54:57], v[162:165], v[182:185], v[54:57]
	v_mfma_f32_16x16x32_bf16 v[50:53], v[170:173], v[182:185], v[50:53]
	v_mfma_f32_16x16x32_bf16 v[38:41], v[162:165], v[200:203], v[38:41]
	v_mfma_f32_16x16x32_bf16 v[34:37], v[170:173], v[200:203], v[34:37]
	v_mfma_f32_16x16x32_bf16 v[22:25], v[162:165], v[208:211], v[22:25]
	v_mfma_f32_16x16x32_bf16 v[18:21], v[170:173], v[208:211], v[18:21]
	v_mfma_f32_16x16x32_bf16 v[6:9], v[162:165], v[216:219], v[6:9]
	v_mfma_f32_16x16x32_bf16 v[2:5], v[170:173], v[216:219], v[2:5]
	s_setprio 0
	s_barrier
	s_add_u32 s40, s40, 0x100
	s_addc_u32 s41, s41, 0
	s_add_u32 s44, s44, 0x100
	s_addc_u32 s45, s45, 0
	s_cmp_ge_i32 s46, s74
	s_mov_b32 s42, s46
	s_cbranch_scc0 .LBB0_467
